# full grid barriers: non-leader workgroups poll the top-level generation word directly instead of the per-XCD relay word
# speedup vs baseline: 1.0032x; 1.0032x over previous
; __device__ __forceinline__ unsigned xb_ld(unsigned* p)              { return __hip_atomic_load(p, __ATOMIC_RELAXED, __HIP_MEMORY_SCOPE_AGENT); }
; __device__ __forceinline__ unsigned xb_add(unsigned* p, unsigned v) { return __hip_atomic_fetch_add(p, v, __ATOMIC_RELAXED, __HIP_MEMORY_SCOPE_AGENT); }
; #define XB_SPIN(cond, bar) do { unsigned _sp = 0; while (cond) { __builtin_amdgcn_s_sleep(1); \
;     if ((++_sp & 255u) == 0u) { if (xb_ld(&(bar)[XB_TMO])) break; if (_sp > XB_SPIN_CAP) { atomicAdd(&(bar)[XB_TMO], 1u); break; } } } } while (0)
; __device__ __forceinline__ void xcd_barrier(const XcdBarrier& b) {
;     ...
;         const unsigned old = xb_add(&bar[XB_XSUB(b.x)], 1u);
;         const unsigned gen = old / nloc;
;         if (old + 1u == (gen + 1u) * nloc) {
;             __builtin_amdgcn_fence(__ATOMIC_RELEASE, "agent");
;             asm volatile("s_waitcnt vmcnt(0)" ::: "memory");
;             const unsigned og = xb_add(&bar[XB_TOP], 1u);
;             const unsigned tg = og / nx;
;             if (og + 1u == (tg + 1u) * nx) xb_add(&bar[XB_TOPGEN], 1u);
;             else XB_SPIN(xb_ld(&bar[XB_TOPGEN]) == tg, bar);
;             __builtin_amdgcn_fence(__ATOMIC_ACQUIRE, "agent");
;             xb_add(&bar[XB_XGEN(b.x)], 1u);
;             asm volatile("s_waitcnt vmcnt(0)" ::: "memory");
;         } else {
;             XB_SPIN(xb_ld(&bar[XB_XGEN(b.x)]) == gen, bar);
.LBB0_282:
	s_or_b64 exec, exec, s[8:9]
	v_cvt_f32_u32_e32 v4, v2
	s_waitcnt vmcnt(0)
	v_readfirstlane_b32 s3, v3
	v_sub_u32_e32 v3, 0, v2
	v_rcp_iflag_f32_e32 v4, v4
	v_add_u32_e32 v5, s3, v1
	v_mul_f32_e32 v4, 0x4f7ffffe, v4
	v_cvt_u32_f32_e32 v4, v4
	v_mul_lo_u32 v1, v3, v4
	v_mul_hi_u32 v1, v4, v1
	v_add_u32_e32 v1, v4, v1
	v_mul_hi_u32 v1, v5, v1
	v_mul_lo_u32 v3, v1, v2
	v_sub_u32_e32 v3, v5, v3
	v_add_u32_e32 v4, 1, v1
	v_cmp_ge_u32_e32 vcc, v3, v2
	s_nop 1
	v_cndmask_b32_e32 v1, v1, v4, vcc
	v_sub_u32_e32 v4, v3, v2
	v_cndmask_b32_e32 v3, v3, v4, vcc
	v_add_u32_e32 v4, 1, v1
	v_cmp_ge_u32_e32 vcc, v3, v2
	v_add_u32_e32 v3, 1, v5
	s_nop 0
	v_cndmask_b32_e32 v1, v1, v4, vcc
	v_mul_lo_u32 v4, v2, v1
	v_add_u32_e32 v2, v4, v2
	v_cmp_ne_u32_e32 vcc, v3, v2
	s_and_saveexec_b64 s[6:7], vcc
	s_xor_b64 s[6:7], exec, s[6:7]
	s_cbranch_execz .LBB0_296
	s_waitcnt lgkmcnt(0)
	v_mov_b32_e32 v0, 0x3100
	global_load_dword v0, v0, s[58:59] offset:1024 sc1
	s_add_u32 s10, s58, 0x3500
	s_addc_u32 s11, s59, 0
	v_mov_b32_e32 v1, 0
	s_waitcnt vmcnt(0)
	v_cmp_eq_u32_e32 vcc, v0, v1
	s_and_saveexec_b64 s[8:9], vcc
	s_cbranch_execz .LBB0_295
	s_mov_b32 s3, 1
	s_mov_b64 s[12:13], 0
	v_mov_b32_e32 v0, 0
	s_branch .LBB0_286

; __device__ __forceinline__ unsigned xb_ld(unsigned* p)              { return __hip_atomic_load(p, __ATOMIC_RELAXED, __HIP_MEMORY_SCOPE_AGENT); }
; __device__ __forceinline__ unsigned xb_add(unsigned* p, unsigned v) { return __hip_atomic_fetch_add(p, v, __ATOMIC_RELAXED, __HIP_MEMORY_SCOPE_AGENT); }
; #define XB_SPIN(cond, bar) do { unsigned _sp = 0; while (cond) { __builtin_amdgcn_s_sleep(1); \
;     if ((++_sp & 255u) == 0u) { if (xb_ld(&(bar)[XB_TMO])) break; if (_sp > XB_SPIN_CAP) { atomicAdd(&(bar)[XB_TMO], 1u); break; } } } } while (0)
; __device__ __forceinline__ void xcd_barrier(const XcdBarrier& b) {
;     ...
;         const unsigned old = xb_add(&bar[XB_XSUB(b.x)], 1u);
;         const unsigned gen = old / nloc;
;         if (old + 1u == (gen + 1u) * nloc) {
;             __builtin_amdgcn_fence(__ATOMIC_RELEASE, "agent");
;             asm volatile("s_waitcnt vmcnt(0)" ::: "memory");
;             const unsigned og = xb_add(&bar[XB_TOP], 1u);
;             const unsigned tg = og / nx;
;             if (og + 1u == (tg + 1u) * nx) xb_add(&bar[XB_TOPGEN], 1u);
;             else XB_SPIN(xb_ld(&bar[XB_TOPGEN]) == tg, bar);
;             __builtin_amdgcn_fence(__ATOMIC_ACQUIRE, "agent");
;             xb_add(&bar[XB_XGEN(b.x)], 1u);
;             asm volatile("s_waitcnt vmcnt(0)" ::: "memory");
;         } else {
;             XB_SPIN(xb_ld(&bar[XB_XGEN(b.x)]) == gen, bar);
.LBB0_470:
	s_or_b64 exec, exec, s[8:9]
	v_cvt_f32_u32_e32 v4, v2
	s_waitcnt vmcnt(0)
	v_readfirstlane_b32 s3, v3
	v_sub_u32_e32 v3, 0, v2
	v_rcp_iflag_f32_e32 v4, v4
	v_add_u32_e32 v5, s3, v1
	v_mul_f32_e32 v4, 0x4f7ffffe, v4
	v_cvt_u32_f32_e32 v4, v4
	v_mul_lo_u32 v1, v3, v4
	v_mul_hi_u32 v1, v4, v1
	v_add_u32_e32 v1, v4, v1
	v_mul_hi_u32 v1, v5, v1
	v_mul_lo_u32 v3, v1, v2
	v_sub_u32_e32 v3, v5, v3
	v_add_u32_e32 v4, 1, v1
	v_cmp_ge_u32_e32 vcc, v3, v2
	s_nop 1
	v_cndmask_b32_e32 v1, v1, v4, vcc
	v_sub_u32_e32 v4, v3, v2
	v_cndmask_b32_e32 v3, v3, v4, vcc
	v_add_u32_e32 v4, 1, v1
	v_cmp_ge_u32_e32 vcc, v3, v2
	v_add_u32_e32 v3, 1, v5
	s_nop 0
	v_cndmask_b32_e32 v1, v1, v4, vcc
	v_mul_lo_u32 v4, v2, v1
	v_add_u32_e32 v2, v4, v2
	v_cmp_ne_u32_e32 vcc, v3, v2
	s_and_saveexec_b64 s[6:7], vcc
	s_xor_b64 s[6:7], exec, s[6:7]
	s_cbranch_execz .LBB0_484
	s_waitcnt lgkmcnt(0)
	v_mov_b32_e32 v0, 0x3100
	global_load_dword v0, v0, s[58:59] offset:1024 sc1
	s_add_u32 s10, s58, 0x3500
	s_addc_u32 s11, s59, 0
	v_mov_b32_e32 v1, 1
	s_waitcnt vmcnt(0)
	v_cmp_eq_u32_e32 vcc, v0, v1
	s_and_saveexec_b64 s[8:9], vcc
	s_cbranch_execz .LBB0_483
	s_mov_b32 s3, 1
	s_mov_b64 s[12:13], 0
	v_mov_b32_e32 v0, 0
	s_branch .LBB0_474

; __device__ __forceinline__ unsigned xb_ld(unsigned* p)              { return __hip_atomic_load(p, __ATOMIC_RELAXED, __HIP_MEMORY_SCOPE_AGENT); }
; __device__ __forceinline__ unsigned xb_add(unsigned* p, unsigned v) { return __hip_atomic_fetch_add(p, v, __ATOMIC_RELAXED, __HIP_MEMORY_SCOPE_AGENT); }
; #define XB_SPIN(cond, bar) do { unsigned _sp = 0; while (cond) { __builtin_amdgcn_s_sleep(1); \
;     if ((++_sp & 255u) == 0u) { if (xb_ld(&(bar)[XB_TMO])) break; if (_sp > XB_SPIN_CAP) { atomicAdd(&(bar)[XB_TMO], 1u); break; } } } } while (0)
; __device__ __forceinline__ void xcd_barrier(const XcdBarrier& b) {
;     ...
;         const unsigned old = xb_add(&bar[XB_XSUB(b.x)], 1u);
;         const unsigned gen = old / nloc;
;         if (old + 1u == (gen + 1u) * nloc) {
;             __builtin_amdgcn_fence(__ATOMIC_RELEASE, "agent");
;             asm volatile("s_waitcnt vmcnt(0)" ::: "memory");
;             const unsigned og = xb_add(&bar[XB_TOP], 1u);
;             const unsigned tg = og / nx;
;             if (og + 1u == (tg + 1u) * nx) xb_add(&bar[XB_TOPGEN], 1u);
;             else XB_SPIN(xb_ld(&bar[XB_TOPGEN]) == tg, bar);
;             __builtin_amdgcn_fence(__ATOMIC_ACQUIRE, "agent");
;             xb_add(&bar[XB_XGEN(b.x)], 1u);
;             asm volatile("s_waitcnt vmcnt(0)" ::: "memory");
;         } else {
;             XB_SPIN(xb_ld(&bar[XB_XGEN(b.x)]) == gen, bar);
.LBB0_689:
	s_or_b64 exec, exec, s[8:9]
	v_cvt_f32_u32_e32 v4, v2
	s_waitcnt vmcnt(0)
	v_readfirstlane_b32 s3, v3
	v_sub_u32_e32 v3, 0, v2
	v_rcp_iflag_f32_e32 v4, v4
	v_add_u32_e32 v5, s3, v1
	v_mul_f32_e32 v4, 0x4f7ffffe, v4
	v_cvt_u32_f32_e32 v4, v4
	v_mul_lo_u32 v1, v3, v4
	v_mul_hi_u32 v1, v4, v1
	v_add_u32_e32 v1, v4, v1
	v_mul_hi_u32 v1, v5, v1
	v_mul_lo_u32 v3, v1, v2
	v_sub_u32_e32 v3, v5, v3
	v_add_u32_e32 v4, 1, v1
	v_cmp_ge_u32_e32 vcc, v3, v2
	s_nop 1
	v_cndmask_b32_e32 v1, v1, v4, vcc
	v_sub_u32_e32 v4, v3, v2
	v_cndmask_b32_e32 v3, v3, v4, vcc
	v_add_u32_e32 v4, 1, v1
	v_cmp_ge_u32_e32 vcc, v3, v2
	v_add_u32_e32 v3, 1, v5
	s_nop 0
	v_cndmask_b32_e32 v1, v1, v4, vcc
	v_mul_lo_u32 v4, v2, v1
	v_add_u32_e32 v2, v4, v2
	v_cmp_ne_u32_e32 vcc, v3, v2
	s_and_saveexec_b64 s[6:7], vcc
	s_xor_b64 s[6:7], exec, s[6:7]
	s_cbranch_execz .LBB0_703
	s_waitcnt lgkmcnt(0)
	v_mov_b32_e32 v0, 0x3100
	global_load_dword v0, v0, s[58:59] offset:1024 sc1
	s_add_u32 s10, s58, 0x3500
	s_addc_u32 s11, s59, 0
	v_readlane_b32 s3, v255, 40
	s_cmp_eq_u32 s3, 0
	s_cselect_b32 s3, 2, 3
	v_mov_b32_e32 v1, s3
	s_waitcnt vmcnt(0)
	v_cmp_eq_u32_e32 vcc, v0, v1
	s_and_saveexec_b64 s[8:9], vcc
	s_cbranch_execz .LBB0_702
	s_mov_b32 s3, 1
	s_mov_b64 s[12:13], 0
	v_mov_b32_e32 v0, 0
	s_branch .LBB0_693

; __device__ __forceinline__ unsigned xb_ld(unsigned* p)              { return __hip_atomic_load(p, __ATOMIC_RELAXED, __HIP_MEMORY_SCOPE_AGENT); }
; __device__ __forceinline__ unsigned xb_add(unsigned* p, unsigned v) { return __hip_atomic_fetch_add(p, v, __ATOMIC_RELAXED, __HIP_MEMORY_SCOPE_AGENT); }
; #define XB_SPIN(cond, bar) do { unsigned _sp = 0; while (cond) { __builtin_amdgcn_s_sleep(1); \
;     if ((++_sp & 255u) == 0u) { if (xb_ld(&(bar)[XB_TMO])) break; if (_sp > XB_SPIN_CAP) { atomicAdd(&(bar)[XB_TMO], 1u); break; } } } } while (0)
; __device__ __forceinline__ void xcd_barrier(const XcdBarrier& b) {
;     ...
;         const unsigned old = xb_add(&bar[XB_XSUB(b.x)], 1u);
;         const unsigned gen = old / nloc;
;         if (old + 1u == (gen + 1u) * nloc) {
;             __builtin_amdgcn_fence(__ATOMIC_RELEASE, "agent");
;             asm volatile("s_waitcnt vmcnt(0)" ::: "memory");
;             const unsigned og = xb_add(&bar[XB_TOP], 1u);
;             const unsigned tg = og / nx;
;             if (og + 1u == (tg + 1u) * nx) xb_add(&bar[XB_TOPGEN], 1u);
;             else XB_SPIN(xb_ld(&bar[XB_TOPGEN]) == tg, bar);
;             __builtin_amdgcn_fence(__ATOMIC_ACQUIRE, "agent");
;             xb_add(&bar[XB_XGEN(b.x)], 1u);
;             asm volatile("s_waitcnt vmcnt(0)" ::: "memory");
;         } else {
;             XB_SPIN(xb_ld(&bar[XB_XGEN(b.x)]) == gen, bar);
.LBB0_970:
	s_or_b64 exec, exec, s[16:17]
	v_cvt_f32_u32_e32 v4, v2
	s_waitcnt vmcnt(0)
	v_readfirstlane_b32 s3, v3
	v_sub_u32_e32 v3, 0, v2
	v_rcp_iflag_f32_e32 v4, v4
	v_add_u32_e32 v5, s3, v1
	v_mul_f32_e32 v4, 0x4f7ffffe, v4
	v_cvt_u32_f32_e32 v4, v4
	v_mul_lo_u32 v1, v3, v4
	v_mul_hi_u32 v1, v4, v1
	v_add_u32_e32 v1, v4, v1
	v_mul_hi_u32 v1, v5, v1
	v_mul_lo_u32 v3, v1, v2
	v_sub_u32_e32 v3, v5, v3
	v_add_u32_e32 v4, 1, v1
	v_cmp_ge_u32_e32 vcc, v3, v2
	s_nop 1
	v_cndmask_b32_e32 v1, v1, v4, vcc
	v_sub_u32_e32 v4, v3, v2
	v_cndmask_b32_e32 v3, v3, v4, vcc
	v_add_u32_e32 v4, 1, v1
	v_cmp_ge_u32_e32 vcc, v3, v2
	v_add_u32_e32 v3, 1, v5
	s_nop 0
	v_cndmask_b32_e32 v1, v1, v4, vcc
	v_mul_lo_u32 v4, v2, v1
	v_add_u32_e32 v2, v4, v2
	v_cmp_ne_u32_e32 vcc, v3, v2
	s_and_saveexec_b64 s[4:5], vcc
	s_xor_b64 s[10:11], exec, s[4:5]
	s_cbranch_execz .LBB0_984
	s_waitcnt lgkmcnt(0)
	v_mov_b32_e32 v0, 0x3100
	global_load_dword v0, v0, s[58:59] offset:1024 sc1
	s_add_u32 s18, s58, 0x3500
	s_addc_u32 s19, s59, 0
	v_readlane_b32 s3, v255, 40
	s_cmp_eq_u32 s3, 0
	s_cselect_b32 s3, 3, 6
	v_mov_b32_e32 v1, s3
	s_waitcnt vmcnt(0)
	v_cmp_eq_u32_e32 vcc, v0, v1
	s_and_saveexec_b64 s[16:17], vcc
	s_cbranch_execz .LBB0_983
	s_mov_b32 s3, 1
	s_mov_b64 s[20:21], 0
	v_mov_b32_e32 v0, 0
	s_branch .LBB0_974

; __device__ __forceinline__ unsigned xb_ld(unsigned* p)              { return __hip_atomic_load(p, __ATOMIC_RELAXED, __HIP_MEMORY_SCOPE_AGENT); }
; __device__ __forceinline__ unsigned xb_add(unsigned* p, unsigned v) { return __hip_atomic_fetch_add(p, v, __ATOMIC_RELAXED, __HIP_MEMORY_SCOPE_AGENT); }
; #define XB_SPIN(cond, bar) do { unsigned _sp = 0; while (cond) { __builtin_amdgcn_s_sleep(1); \
;     if ((++_sp & 255u) == 0u) { if (xb_ld(&(bar)[XB_TMO])) break; if (_sp > XB_SPIN_CAP) { atomicAdd(&(bar)[XB_TMO], 1u); break; } } } } while (0)
; __device__ __forceinline__ void xcd_barrier(const XcdBarrier& b) {
;     ...
;         const unsigned old = xb_add(&bar[XB_XSUB(b.x)], 1u);
;         const unsigned gen = old / nloc;
;         if (old + 1u == (gen + 1u) * nloc) {
;             __builtin_amdgcn_fence(__ATOMIC_RELEASE, "agent");
;             asm volatile("s_waitcnt vmcnt(0)" ::: "memory");
;             const unsigned og = xb_add(&bar[XB_TOP], 1u);
;             const unsigned tg = og / nx;
;             if (og + 1u == (tg + 1u) * nx) xb_add(&bar[XB_TOPGEN], 1u);
;             else XB_SPIN(xb_ld(&bar[XB_TOPGEN]) == tg, bar);
;             __builtin_amdgcn_fence(__ATOMIC_ACQUIRE, "agent");
;             xb_add(&bar[XB_XGEN(b.x)], 1u);
;             asm volatile("s_waitcnt vmcnt(0)" ::: "memory");
;         } else {
;             XB_SPIN(xb_ld(&bar[XB_XGEN(b.x)]) == gen, bar);
.LBB0_1182:
	s_or_b64 exec, exec, s[16:17]
	v_cvt_f32_u32_e32 v4, v2
	s_waitcnt vmcnt(0)
	v_readfirstlane_b32 s3, v3
	v_sub_u32_e32 v3, 0, v2
	v_rcp_iflag_f32_e32 v4, v4
	v_add_u32_e32 v5, s3, v1
	v_mul_f32_e32 v4, 0x4f7ffffe, v4
	v_cvt_u32_f32_e32 v4, v4
	v_mul_lo_u32 v1, v3, v4
	v_mul_hi_u32 v1, v4, v1
	v_add_u32_e32 v1, v4, v1
	v_mul_hi_u32 v1, v5, v1
	v_mul_lo_u32 v3, v1, v2
	v_sub_u32_e32 v3, v5, v3
	v_add_u32_e32 v4, 1, v1
	v_cmp_ge_u32_e32 vcc, v3, v2
	s_nop 1
	v_cndmask_b32_e32 v1, v1, v4, vcc
	v_sub_u32_e32 v4, v3, v2
	v_cndmask_b32_e32 v3, v3, v4, vcc
	v_add_u32_e32 v4, 1, v1
	v_cmp_ge_u32_e32 vcc, v3, v2
	v_add_u32_e32 v3, 1, v5
	s_nop 0
	v_cndmask_b32_e32 v1, v1, v4, vcc
	v_mul_lo_u32 v4, v2, v1
	v_add_u32_e32 v2, v4, v2
	v_cmp_ne_u32_e32 vcc, v3, v2
	s_and_saveexec_b64 s[4:5], vcc
	s_xor_b64 s[10:11], exec, s[4:5]
	s_cbranch_execz .LBB0_1196
	s_waitcnt lgkmcnt(0)
	v_mov_b32_e32 v0, 0x3100
	global_load_dword v0, v0, s[58:59] offset:1024 sc1
	s_add_u32 s18, s58, 0x3500
	s_addc_u32 s19, s59, 0
	v_readlane_b32 s3, v255, 40
	s_cmp_eq_u32 s3, 0
	s_cselect_b32 s3, 4, 7
	v_mov_b32_e32 v1, s3
	s_waitcnt vmcnt(0)
	v_cmp_eq_u32_e32 vcc, v0, v1
	s_and_saveexec_b64 s[16:17], vcc
	s_cbranch_execz .LBB0_1195
	s_mov_b32 s3, 1
	s_mov_b64 s[20:21], 0
	v_mov_b32_e32 v0, 0
	s_branch .LBB0_1186

; __device__ __forceinline__ unsigned xb_ld(unsigned* p)              { return __hip_atomic_load(p, __ATOMIC_RELAXED, __HIP_MEMORY_SCOPE_AGENT); }
; __device__ __forceinline__ unsigned xb_add(unsigned* p, unsigned v) { return __hip_atomic_fetch_add(p, v, __ATOMIC_RELAXED, __HIP_MEMORY_SCOPE_AGENT); }
; #define XB_SPIN(cond, bar) do { unsigned _sp = 0; while (cond) { __builtin_amdgcn_s_sleep(1); \
;     if ((++_sp & 255u) == 0u) { if (xb_ld(&(bar)[XB_TMO])) break; if (_sp > XB_SPIN_CAP) { atomicAdd(&(bar)[XB_TMO], 1u); break; } } } } while (0)
; __device__ __forceinline__ void xcd_barrier(const XcdBarrier& b) {
;     ...
;         const unsigned old = xb_add(&bar[XB_XSUB(b.x)], 1u);
;         const unsigned gen = old / nloc;
;         if (old + 1u == (gen + 1u) * nloc) {
;             __builtin_amdgcn_fence(__ATOMIC_RELEASE, "agent");
;             asm volatile("s_waitcnt vmcnt(0)" ::: "memory");
;             const unsigned og = xb_add(&bar[XB_TOP], 1u);
;             const unsigned tg = og / nx;
;             if (og + 1u == (tg + 1u) * nx) xb_add(&bar[XB_TOPGEN], 1u);
;             else XB_SPIN(xb_ld(&bar[XB_TOPGEN]) == tg, bar);
;             __builtin_amdgcn_fence(__ATOMIC_ACQUIRE, "agent");
;             xb_add(&bar[XB_XGEN(b.x)], 1u);
;             asm volatile("s_waitcnt vmcnt(0)" ::: "memory");
;         } else {
;             XB_SPIN(xb_ld(&bar[XB_XGEN(b.x)]) == gen, bar);
.LBB0_1303:
	s_or_b64 exec, exec, s[12:13]
	v_cvt_f32_u32_e32 v4, v2
	s_waitcnt vmcnt(0)
	v_readfirstlane_b32 s3, v3
	v_sub_u32_e32 v3, 0, v2
	v_rcp_iflag_f32_e32 v4, v4
	v_add_u32_e32 v5, s3, v1
	v_mul_f32_e32 v4, 0x4f7ffffe, v4
	v_cvt_u32_f32_e32 v4, v4
	v_mul_lo_u32 v1, v3, v4
	v_mul_hi_u32 v1, v4, v1
	v_add_u32_e32 v1, v4, v1
	v_mul_hi_u32 v1, v5, v1
	v_mul_lo_u32 v3, v1, v2
	v_sub_u32_e32 v3, v5, v3
	v_add_u32_e32 v4, 1, v1
	v_cmp_ge_u32_e32 vcc, v3, v2
	s_nop 1
	v_cndmask_b32_e32 v1, v1, v4, vcc
	v_sub_u32_e32 v4, v3, v2
	v_cndmask_b32_e32 v3, v3, v4, vcc
	v_add_u32_e32 v4, 1, v1
	v_cmp_ge_u32_e32 vcc, v3, v2
	v_add_u32_e32 v3, 1, v5
	s_nop 0
	v_cndmask_b32_e32 v1, v1, v4, vcc
	v_mul_lo_u32 v4, v2, v1
	v_add_u32_e32 v2, v4, v2
	v_cmp_ne_u32_e32 vcc, v3, v2
	s_and_saveexec_b64 s[4:5], vcc
	s_xor_b64 s[10:11], exec, s[4:5]
	s_cbranch_execz .LBB0_1317
	s_waitcnt lgkmcnt(0)
	v_mov_b32_e32 v0, 0x3100
	global_load_dword v0, v0, s[58:59] offset:1024 sc1
	s_add_u32 s14, s58, 0x3500
	s_addc_u32 s15, s59, 0
	v_readlane_b32 s3, v255, 40
	s_cmp_eq_u32 s3, 0
	s_cselect_b32 s3, 5, 8
	v_mov_b32_e32 v1, s3
	s_waitcnt vmcnt(0)
	v_cmp_eq_u32_e32 vcc, v0, v1
	s_and_saveexec_b64 s[12:13], vcc
	s_cbranch_execz .LBB0_1316
	s_mov_b32 s3, 1
	s_mov_b64 s[20:21], 0
	v_mov_b32_e32 v0, 0
	s_branch .LBB0_1307

; __device__ __forceinline__ unsigned xb_ld(unsigned* p)              { return __hip_atomic_load(p, __ATOMIC_RELAXED, __HIP_MEMORY_SCOPE_AGENT); }
; __device__ __forceinline__ unsigned xb_add(unsigned* p, unsigned v) { return __hip_atomic_fetch_add(p, v, __ATOMIC_RELAXED, __HIP_MEMORY_SCOPE_AGENT); }
; #define XB_SPIN(cond, bar) do { unsigned _sp = 0; while (cond) { __builtin_amdgcn_s_sleep(1); \
;     if ((++_sp & 255u) == 0u) { if (xb_ld(&(bar)[XB_TMO])) break; if (_sp > XB_SPIN_CAP) { atomicAdd(&(bar)[XB_TMO], 1u); break; } } } } while (0)
; __device__ __forceinline__ void xcd_barrier(const XcdBarrier& b) {
;     ...
;         const unsigned old = xb_add(&bar[XB_XSUB(b.x)], 1u);
;         const unsigned gen = old / nloc;
;         if (old + 1u == (gen + 1u) * nloc) {
;             __builtin_amdgcn_fence(__ATOMIC_RELEASE, "agent");
;             asm volatile("s_waitcnt vmcnt(0)" ::: "memory");
;             const unsigned og = xb_add(&bar[XB_TOP], 1u);
;             const unsigned tg = og / nx;
;             if (og + 1u == (tg + 1u) * nx) xb_add(&bar[XB_TOPGEN], 1u);
;             else XB_SPIN(xb_ld(&bar[XB_TOPGEN]) == tg, bar);
;             __builtin_amdgcn_fence(__ATOMIC_ACQUIRE, "agent");
;             xb_add(&bar[XB_XGEN(b.x)], 1u);
;             asm volatile("s_waitcnt vmcnt(0)" ::: "memory");
;         } else {
;             XB_SPIN(xb_ld(&bar[XB_XGEN(b.x)]) == gen, bar);
.LBB0_1507:
	s_or_b64 exec, exec, s[6:7]
	v_cvt_f32_u32_e32 v4, v2
	s_waitcnt vmcnt(0)
	v_readfirstlane_b32 s4, v3
	v_sub_u32_e32 v3, 0, v2
	v_rcp_iflag_f32_e32 v4, v4
	v_add_u32_e32 v5, s4, v1
	v_mul_f32_e32 v4, 0x4f7ffffe, v4
	v_cvt_u32_f32_e32 v4, v4
	v_mul_lo_u32 v1, v3, v4
	v_mul_hi_u32 v1, v4, v1
	v_add_u32_e32 v1, v4, v1
	v_mul_hi_u32 v1, v5, v1
	v_mul_lo_u32 v3, v1, v2
	v_sub_u32_e32 v3, v5, v3
	v_add_u32_e32 v4, 1, v1
	v_cmp_ge_u32_e32 vcc, v3, v2
	s_nop 1
	v_cndmask_b32_e32 v1, v1, v4, vcc
	v_sub_u32_e32 v4, v3, v2
	v_cndmask_b32_e32 v3, v3, v4, vcc
	v_add_u32_e32 v4, 1, v1
	v_cmp_ge_u32_e32 vcc, v3, v2
	v_add_u32_e32 v3, 1, v5
	s_nop 0
	v_cndmask_b32_e32 v1, v1, v4, vcc
	v_mul_lo_u32 v4, v2, v1
	v_add_u32_e32 v2, v4, v2
	v_cmp_ne_u32_e32 vcc, v3, v2
	s_and_saveexec_b64 s[4:5], vcc
	s_xor_b64 s[4:5], exec, s[4:5]
	s_cbranch_execz .LBB0_1521
	s_waitcnt lgkmcnt(0)
	v_mov_b32_e32 v0, 0x3100
	global_load_dword v0, v0, s[58:59] offset:1024 sc1
	s_add_u32 s8, s58, 0x3500
	s_addc_u32 s9, s59, 0
	v_readlane_b32 s3, v255, 40
	s_cmp_eq_u32 s3, 0
	s_cselect_b32 s3, 6, 10
	v_mov_b32_e32 v1, s3
	s_waitcnt vmcnt(0)
	v_cmp_eq_u32_e32 vcc, v0, v1
	s_and_saveexec_b64 s[6:7], vcc
	s_cbranch_execz .LBB0_1520
	s_mov_b32 s20, 1
	s_mov_b64 s[10:11], 0
	v_mov_b32_e32 v0, 0
	s_branch .LBB0_1511
